# P3 GLU sample row block GEMM: K loop unrolled into 8 half-steps over three operand register sets, two half-steps of loads in flight (was one)
# speedup vs baseline: 1.0049x; 1.0049x over previous
; #define SGT_LOAD(S_, KS_) do { _Pragma("unroll") for (int u = 0; u < U; ++u) { a0[S_][u] = *(const bf16x8*)(ap + (KS_) + 32 * u); if (MB == 2) a1[S_][u] = *(const bf16x8*)(ap + (size_t)16 * lda + (KS_) + 32 * u); \
;         _Pragma("unroll") for (int n = 0; n < NBW; ++n) b[S_][u][n] = *(const bf16x8*)(bp + (size_t)n * 16 * K + (KS_) + 32 * u); } } while (0)
; #define SGT_MMA(S_) do { _Pragma("unroll") for (int u = 0; u < U; ++u) _Pragma("unroll") for (int n = 0; n < NBW; ++n) { acc[0][n] = __builtin_amdgcn_mfma_f32_16x16x32_bf16(b[S_][u][n], a0[S_][u], acc[0][n], 0, 0, 0); \
;         if (MB == 2) acc[MB - 1][n] = __builtin_amdgcn_mfma_f32_16x16x32_bf16(b[S_][u][n], a1[S_][u], acc[MB - 1][n], 0, 0, 0); } } while (0)
;     ...
;     const int lane = tid & 63, wave = __builtin_amdgcn_readfirstlane(tid >> 6), wk = wave / WN, wn = wave % WN, fr = lane & 15, fq = lane >> 4;
;     const int k0 = wk * KPER;
;     f32x4 acc[MB][NBW];
; #pragma unroll
;     for (int m = 0; m < MB; ++m)
; #pragma unroll
;         for (int n = 0; n < NBW; ++n) acc[m][n] = (f32x4){0.f, 0.f, 0.f, 0.f};
;     const bf16* ap = A + (size_t)(row0 + fr) * lda + k0 + 8 * fq;
;     const bf16* bp = Bt + (size_t)(col0 + wn * (TN / WN) + fr) * K + k0 + 8 * fq;
;     bf16x8 a0[2][U], a1[2][U], b[2][U][NBW];
;     ...
;     constexpr bool ONEPASS = 16 * MB * (TN / 4) <= NWAVES * 64;
;     typename F::Pre pre{};
;     if constexpr (ONEPASS) { if (tid < 16 * MB * (TN / 4)) pre = f.prefetch(tid / (TN / 4), 4 * (tid % (TN / 4))); }
;     SGT_LOAD(0, 0);
; #pragma unroll 1
;     for (int ks = 0; ks < KPER; ks += 64 * U) {
;         if (ks + 32 * U < KPER) SGT_LOAD(1, ks + 32 * U);
;         SGT_MMA(0);
;         if (ks + 64 * U < KPER) SGT_LOAD(0, ks + 64 * U);
;         if (ks + 32 * U < KPER) SGT_MMA(1);
;     }
.LBB0_1061:
	s_cmpk_gt_u32 s26, 0xff
	s_mov_b64 s[4:5], -1
	s_cbranch_scc0 .LBB0_1070
	v_readfirstlane_b32 s6, v160
	s_ashr_i32 s6, s6, 6
	s_ashr_i32 s7, s6, 31
	s_lshr_b32 s7, s7, 29
	s_lshl_b32 s27, s26, 4
	s_add_i32 s7, s6, s7
	s_addk_i32 s27, 0x3000
	s_ashr_i32 s28, s7, 3
	s_and_b32 s7, s7, 0x3fffff8
	s_sub_i32 s14, s6, s7
	s_lshl_b32 s6, s28, 9
	v_or_b32_e32 v2, s27, v132
	v_lshlrev_b32_e32 v2, 10, v2
	s_ashr_i32 s7, s6, 31
	v_lshl_add_u64 v[4:5], s[8:9], 0, v[2:3]
	s_lshl_b64 s[6:7], s[6:7], 1
	v_lshl_add_u64 v[4:5], v[4:5], 0, s[6:7]
	v_mov_b32_e32 v123, v3
	s_lshl_b32 s29, s14, 6
	v_lshl_add_u64 v[8:9], v[4:5], 0, v[122:123]
	v_or_b32_e32 v4, s29, v132
	v_ashrrev_i32_e32 v5, 31, v4
	v_lshlrev_b64 v[44:45], 10, v[4:5]
	v_lshl_add_u64 v[4:5], s[20:21], 0, v[44:45]
	v_lshl_add_u64 v[4:5], v[4:5], 0, s[6:7]
	s_waitcnt vmcnt(0)
	v_lshl_add_u64 v[16:17], v[4:5], 0, v[122:123]
	s_movk_i32 s14, 0x4000
	v_add_co_u32_e32 v24, vcc, s14, v16
	s_mov_b32 s14, 0x8000
	s_nop 0
	v_addc_co_u32_e32 v25, vcc, 0, v17, vcc
	v_add_co_u32_e32 v32, vcc, s14, v16
	v_readlane_b32 s68, v252, 26
	s_nop 0
	v_addc_co_u32_e32 v33, vcc, 0, v17, vcc
	v_readlane_b32 s70, v252, 28
	v_readlane_b32 s71, v252, 29
	v_add_co_u32_e32 v40, vcc, 0xc000, v16
	s_mov_b64 s[4:5], s[70:71]
	s_nop 0
	v_addc_co_u32_e32 v41, vcc, 0, v17, vcc
	v_mov_b64_e32 v[192:193], v[8:9]
	v_mov_b64_e32 v[194:195], v[16:17]
	v_mov_b64_e32 v[196:197], v[24:25]
	v_mov_b64_e32 v[198:199], v[32:33]
	v_mov_b64_e32 v[200:201], v[40:41]
	global_load_dwordx4 v[4:7], v[192:193], off
	global_load_dwordx4 v[8:11], v[192:193], off offset:64
	global_load_dwordx4 v[12:15], v[194:195], off
	global_load_dwordx4 v[16:19], v[194:195], off offset:64
	global_load_dwordx4 v[20:23], v[196:197], off
	global_load_dwordx4 v[24:27], v[196:197], off offset:64
	global_load_dwordx4 v[28:31], v[198:199], off
	global_load_dwordx4 v[32:35], v[198:199], off offset:64
	global_load_dwordx4 v[36:39], v[200:201], off
	global_load_dwordx4 v[40:43], v[200:201], off offset:64
	global_load_dwordx4 v[60:63], v[192:193], off offset:128
	global_load_dwordx4 v[64:67], v[192:193], off offset:192
	global_load_dwordx4 v[68:71], v[194:195], off offset:128
	global_load_dwordx4 v[72:75], v[194:195], off offset:192
	global_load_dwordx4 v[76:79], v[196:197], off offset:128
	global_load_dwordx4 v[80:83], v[196:197], off offset:192
	global_load_dwordx4 v[84:87], v[198:199], off offset:128
	global_load_dwordx4 v[88:91], v[198:199], off offset:192
	global_load_dwordx4 v[92:95], v[200:201], off offset:128
	global_load_dwordx4 v[96:99], v[200:201], off offset:192
	v_mov_b32_e32 v44, 0
	v_mov_b32_e32 v45, v44
	v_mov_b32_e32 v46, v44
	v_mov_b32_e32 v47, v44
	v_mov_b32_e32 v52, v44
	v_mov_b32_e32 v53, v44
	v_mov_b32_e32 v54, v44
	v_mov_b32_e32 v55, v44
	v_mov_b32_e32 v48, v44
	v_mov_b32_e32 v49, v44
	v_mov_b32_e32 v50, v44
	v_mov_b32_e32 v51, v44
	v_mov_b32_e32 v56, v44
	v_mov_b32_e32 v57, v44
	v_mov_b32_e32 v58, v44
	v_mov_b32_e32 v59, v44
	v_readlane_b32 s69, v252, 27
	v_readlane_b32 s72, v252, 30
	v_readlane_b32 s73, v252, 31
	v_readlane_b32 s74, v252, 32
	v_readlane_b32 s75, v252, 33
	v_readlane_b32 s76, v252, 34
	v_readlane_b32 s77, v252, 35
	v_readlane_b32 s78, v252, 36
	v_readlane_b32 s79, v252, 37
	v_readlane_b32 s80, v252, 38
	v_readlane_b32 s81, v252, 39
	v_readlane_b32 s82, v252, 40
	v_readlane_b32 s83, v252, 41
	global_load_dwordx4 v[212:215], v[192:193], off offset:256
	global_load_dwordx4 v[216:219], v[192:193], off offset:320
	global_load_dwordx4 v[220:223], v[194:195], off offset:256
	global_load_dwordx4 v[224:227], v[194:195], off offset:320
	global_load_dwordx4 v[228:231], v[196:197], off offset:256
	global_load_dwordx4 v[232:235], v[196:197], off offset:320
	global_load_dwordx4 v[236:239], v[198:199], off offset:256
	global_load_dwordx4 v[240:243], v[198:199], off offset:320
	global_load_dwordx4 v[184:187], v[200:201], off offset:256
	global_load_dwordx4 v[188:191], v[200:201], off offset:320
	s_waitcnt vmcnt(20)
	v_mfma_f32_16x16x32_bf16 v[44:47], v[12:15], v[4:7], v[44:47]
	v_mfma_f32_16x16x32_bf16 v[52:55], v[20:23], v[4:7], v[52:55]
	v_mfma_f32_16x16x32_bf16 v[48:51], v[28:31], v[4:7], v[48:51]
	v_mfma_f32_16x16x32_bf16 v[56:59], v[36:39], v[4:7], v[56:59]
	v_mfma_f32_16x16x32_bf16 v[44:47], v[16:19], v[8:11], v[44:47]
	v_mfma_f32_16x16x32_bf16 v[52:55], v[24:27], v[8:11], v[52:55]
	v_mfma_f32_16x16x32_bf16 v[48:51], v[32:35], v[8:11], v[48:51]
	v_mfma_f32_16x16x32_bf16 v[56:59], v[40:43], v[8:11], v[56:59]
	global_load_dwordx4 v[4:7], v[192:193], off offset:384
	global_load_dwordx4 v[8:11], v[192:193], off offset:448
	global_load_dwordx4 v[12:15], v[194:195], off offset:384
	global_load_dwordx4 v[16:19], v[194:195], off offset:448
	global_load_dwordx4 v[20:23], v[196:197], off offset:384
	global_load_dwordx4 v[24:27], v[196:197], off offset:448
	global_load_dwordx4 v[28:31], v[198:199], off offset:384
	global_load_dwordx4 v[32:35], v[198:199], off offset:448
	global_load_dwordx4 v[36:39], v[200:201], off offset:384
	global_load_dwordx4 v[40:43], v[200:201], off offset:448
	s_waitcnt vmcnt(20)
; #define SGT_LOAD(S_, KS_) do { _Pragma("unroll") for (int u = 0; u < U; ++u) { a0[S_][u] = *(const bf16x8*)(ap + (KS_) + 32 * u); if (MB == 2) a1[S_][u] = *(const bf16x8*)(ap + (size_t)16 * lda + (KS_) + 32 * u); \
;         _Pragma("unroll") for (int n = 0; n < NBW; ++n) b[S_][u][n] = *(const bf16x8*)(bp + (size_t)n * 16 * K + (KS_) + 32 * u); } } while (0)
; #define SGT_MMA(S_) do { _Pragma("unroll") for (int u = 0; u < U; ++u) _Pragma("unroll") for (int n = 0; n < NBW; ++n) { acc[0][n] = __builtin_amdgcn_mfma_f32_16x16x32_bf16(b[S_][u][n], a0[S_][u], acc[0][n], 0, 0, 0); \
;         if (MB == 2) acc[MB - 1][n] = __builtin_amdgcn_mfma_f32_16x16x32_bf16(b[S_][u][n], a1[S_][u], acc[MB - 1][n], 0, 0, 0); } } while (0)
;     ...
;     const bf16* ap = A + (size_t)(row0 + fr) * lda + k0 + 8 * fq;
;     const bf16* bp = Bt + (size_t)(col0 + wn * (TN / WN) + fr) * K + k0 + 8 * fq;
;     bf16x8 a0[2][U], a1[2][U], b[2][U][NBW];
;     ...
;     constexpr bool ONEPASS = 16 * MB * (TN / 4) <= NWAVES * 64;
;     typename F::Pre pre{};
;     if constexpr (ONEPASS) { if (tid < 16 * MB * (TN / 4)) pre = f.prefetch(tid / (TN / 4), 4 * (tid % (TN / 4))); }
;     SGT_LOAD(0, 0);
; #pragma unroll 1
;     for (int ks = 0; ks < KPER; ks += 64 * U) {
;         if (ks + 32 * U < KPER) SGT_LOAD(1, ks + 32 * U);
;         SGT_MMA(0);
;         if (ks + 64 * U < KPER) SGT_LOAD(0, ks + 64 * U);
;         if (ks + 32 * U < KPER) SGT_MMA(1);
;     }
	v_mfma_f32_16x16x32_bf16 v[44:47], v[68:71], v[60:63], v[44:47]
	v_mfma_f32_16x16x32_bf16 v[52:55], v[76:79], v[60:63], v[52:55]
	v_mfma_f32_16x16x32_bf16 v[48:51], v[84:87], v[60:63], v[48:51]
	v_mfma_f32_16x16x32_bf16 v[56:59], v[92:95], v[60:63], v[56:59]
	v_mfma_f32_16x16x32_bf16 v[44:47], v[72:75], v[64:67], v[44:47]
	v_mfma_f32_16x16x32_bf16 v[52:55], v[80:83], v[64:67], v[52:55]
	v_mfma_f32_16x16x32_bf16 v[48:51], v[88:91], v[64:67], v[48:51]
	v_mfma_f32_16x16x32_bf16 v[56:59], v[96:99], v[64:67], v[56:59]
	global_load_dwordx4 v[60:63], v[192:193], off offset:512
	global_load_dwordx4 v[64:67], v[192:193], off offset:576
	global_load_dwordx4 v[68:71], v[194:195], off offset:512
	global_load_dwordx4 v[72:75], v[194:195], off offset:576
	global_load_dwordx4 v[76:79], v[196:197], off offset:512
	global_load_dwordx4 v[80:83], v[196:197], off offset:576
	global_load_dwordx4 v[84:87], v[198:199], off offset:512
	global_load_dwordx4 v[88:91], v[198:199], off offset:576
	global_load_dwordx4 v[92:95], v[200:201], off offset:512
	global_load_dwordx4 v[96:99], v[200:201], off offset:576
	s_waitcnt vmcnt(20)
	v_mfma_f32_16x16x32_bf16 v[44:47], v[220:223], v[212:215], v[44:47]
	v_mfma_f32_16x16x32_bf16 v[52:55], v[228:231], v[212:215], v[52:55]
	v_mfma_f32_16x16x32_bf16 v[48:51], v[236:239], v[212:215], v[48:51]
	v_mfma_f32_16x16x32_bf16 v[56:59], v[184:187], v[212:215], v[56:59]
	v_mfma_f32_16x16x32_bf16 v[44:47], v[224:227], v[216:219], v[44:47]
	v_mfma_f32_16x16x32_bf16 v[52:55], v[232:235], v[216:219], v[52:55]
	v_mfma_f32_16x16x32_bf16 v[48:51], v[240:243], v[216:219], v[48:51]
	v_mfma_f32_16x16x32_bf16 v[56:59], v[188:191], v[216:219], v[56:59]
	global_load_dwordx4 v[212:215], v[192:193], off offset:640
	global_load_dwordx4 v[216:219], v[192:193], off offset:704
	global_load_dwordx4 v[220:223], v[194:195], off offset:640
	global_load_dwordx4 v[224:227], v[194:195], off offset:704
	global_load_dwordx4 v[228:231], v[196:197], off offset:640
	global_load_dwordx4 v[232:235], v[196:197], off offset:704
	global_load_dwordx4 v[236:239], v[198:199], off offset:640
	global_load_dwordx4 v[240:243], v[198:199], off offset:704
	global_load_dwordx4 v[184:187], v[200:201], off offset:640
	global_load_dwordx4 v[188:191], v[200:201], off offset:704
	s_waitcnt vmcnt(20)
	v_mfma_f32_16x16x32_bf16 v[44:47], v[12:15], v[4:7], v[44:47]
	v_mfma_f32_16x16x32_bf16 v[52:55], v[20:23], v[4:7], v[52:55]
	v_mfma_f32_16x16x32_bf16 v[48:51], v[28:31], v[4:7], v[48:51]
	v_mfma_f32_16x16x32_bf16 v[56:59], v[36:39], v[4:7], v[56:59]
	v_mfma_f32_16x16x32_bf16 v[44:47], v[16:19], v[8:11], v[44:47]
	v_mfma_f32_16x16x32_bf16 v[52:55], v[24:27], v[8:11], v[52:55]
	v_mfma_f32_16x16x32_bf16 v[48:51], v[32:35], v[8:11], v[48:51]
	v_mfma_f32_16x16x32_bf16 v[56:59], v[40:43], v[8:11], v[56:59]
	global_load_dwordx4 v[4:7], v[192:193], off offset:768
	global_load_dwordx4 v[8:11], v[192:193], off offset:832
	global_load_dwordx4 v[12:15], v[194:195], off offset:768
	global_load_dwordx4 v[16:19], v[194:195], off offset:832
	global_load_dwordx4 v[20:23], v[196:197], off offset:768
	global_load_dwordx4 v[24:27], v[196:197], off offset:832
	global_load_dwordx4 v[28:31], v[198:199], off offset:768
	global_load_dwordx4 v[32:35], v[198:199], off offset:832
	global_load_dwordx4 v[36:39], v[200:201], off offset:768
	global_load_dwordx4 v[40:43], v[200:201], off offset:832
	s_waitcnt vmcnt(20)
	v_mfma_f32_16x16x32_bf16 v[44:47], v[68:71], v[60:63], v[44:47]
	v_mfma_f32_16x16x32_bf16 v[52:55], v[76:79], v[60:63], v[52:55]
	v_mfma_f32_16x16x32_bf16 v[48:51], v[84:87], v[60:63], v[48:51]
	v_mfma_f32_16x16x32_bf16 v[56:59], v[92:95], v[60:63], v[56:59]
	v_mfma_f32_16x16x32_bf16 v[44:47], v[72:75], v[64:67], v[44:47]
	v_mfma_f32_16x16x32_bf16 v[52:55], v[80:83], v[64:67], v[52:55]
	v_mfma_f32_16x16x32_bf16 v[48:51], v[88:91], v[64:67], v[48:51]
	v_mfma_f32_16x16x32_bf16 v[56:59], v[96:99], v[64:67], v[56:59]
	global_load_dwordx4 v[60:63], v[192:193], off offset:896
	global_load_dwordx4 v[64:67], v[192:193], off offset:960
	global_load_dwordx4 v[68:71], v[194:195], off offset:896
	global_load_dwordx4 v[72:75], v[194:195], off offset:960
	global_load_dwordx4 v[76:79], v[196:197], off offset:896
	global_load_dwordx4 v[80:83], v[196:197], off offset:960
	global_load_dwordx4 v[84:87], v[198:199], off offset:896
	global_load_dwordx4 v[88:91], v[198:199], off offset:960
	global_load_dwordx4 v[92:95], v[200:201], off offset:896
	global_load_dwordx4 v[96:99], v[200:201], off offset:960
	s_waitcnt vmcnt(20)
	v_mfma_f32_16x16x32_bf16 v[44:47], v[220:223], v[212:215], v[44:47]
	v_mfma_f32_16x16x32_bf16 v[52:55], v[228:231], v[212:215], v[52:55]
	v_mfma_f32_16x16x32_bf16 v[48:51], v[236:239], v[212:215], v[48:51]
	v_mfma_f32_16x16x32_bf16 v[56:59], v[184:187], v[212:215], v[56:59]
	v_mfma_f32_16x16x32_bf16 v[44:47], v[224:227], v[216:219], v[44:47]
	v_mfma_f32_16x16x32_bf16 v[52:55], v[232:235], v[216:219], v[52:55]
	v_mfma_f32_16x16x32_bf16 v[48:51], v[240:243], v[216:219], v[48:51]
	v_mfma_f32_16x16x32_bf16 v[56:59], v[188:191], v[216:219], v[56:59]
	s_waitcnt vmcnt(10)
	v_mfma_f32_16x16x32_bf16 v[44:47], v[12:15], v[4:7], v[44:47]
	v_mfma_f32_16x16x32_bf16 v[52:55], v[20:23], v[4:7], v[52:55]
	v_mfma_f32_16x16x32_bf16 v[48:51], v[28:31], v[4:7], v[48:51]
	v_mfma_f32_16x16x32_bf16 v[56:59], v[36:39], v[4:7], v[56:59]
	v_mfma_f32_16x16x32_bf16 v[44:47], v[16:19], v[8:11], v[44:47]
	v_mfma_f32_16x16x32_bf16 v[52:55], v[24:27], v[8:11], v[52:55]
	v_mfma_f32_16x16x32_bf16 v[48:51], v[32:35], v[8:11], v[48:51]
	v_mfma_f32_16x16x32_bf16 v[56:59], v[40:43], v[8:11], v[56:59]
	s_waitcnt vmcnt(0)
	v_mfma_f32_16x16x32_bf16 v[44:47], v[68:71], v[60:63], v[44:47]
	v_mfma_f32_16x16x32_bf16 v[52:55], v[76:79], v[60:63], v[52:55]
	v_mfma_f32_16x16x32_bf16 v[48:51], v[84:87], v[60:63], v[48:51]
	v_mfma_f32_16x16x32_bf16 v[56:59], v[92:95], v[60:63], v[56:59]
	v_mfma_f32_16x16x32_bf16 v[44:47], v[72:75], v[64:67], v[44:47]
	v_mfma_f32_16x16x32_bf16 v[52:55], v[80:83], v[64:67], v[52:55]
	v_mfma_f32_16x16x32_bf16 v[48:51], v[88:91], v[64:67], v[48:51]
	v_mfma_f32_16x16x32_bf16 v[56:59], v[96:99], v[64:67], v[56:59]
	s_mov_b64 s[94:95], 0x100
	s_mov_b64 s[34:35], 0x100
	s_mov_b64 s[14:15], -1
	s_nop 7
